# speedup vs baseline: 1.0255x; 1.0034x over previous
; #define SCAN_BAR() do { asm volatile("s_waitcnt lgkmcnt(0)" ::: "memory"); __builtin_amdgcn_s_barrier(); asm volatile("" ::: "memory"); } while (0)
; __device__ __forceinline__ void scan_phase(const ScanArgs& s, char* shm) {
;     ...
;     } else if (wid < 6) {
;       const int yw = wid - 2, sw = yw & 1, tp = yw >> 1;
;       const int rr = lane >> 4, j = lane & 15, row = sw * 4 + rr;
;       u16* yp = s.Y + tokb * 1024 + colh + rg * 8 + (lane & 1) * 4;
;       SCAN_BAR();
.LBB0_154:
	s_andn2_saveexec_b64 s[60:61], s[74:75]
	s_cbranch_execz .LBB0_168
	s_setprio 1
	s_lshl_b64 s[62:63], s[62:63], 25
	s_add_u32 s62, s44, s62
	s_addc_u32 s63, s39, s63
	s_lshl_b32 s65, s65, 1
	s_add_u32 s62, s62, s65
	s_addc_u32 s63, s63, 0
	s_lshl_b32 s65, s64, 4
	s_add_u32 s62, s62, s65
	s_addc_u32 s63, s63, 0
	v_mov_b32_e32 v141, v133
	s_cmp_eq_u32 s64, 0
	v_lshl_add_u64 v[0:1], s[62:63], 0, v[140:141]
	s_cselect_b64 s[62:63], -1, 0
	s_waitcnt lgkmcnt(0)
	s_barrier
	s_and_b64 s[62:63], s[62:63], s[14:15]
	s_lshl_b32 s49, s49, 2
	s_add_u32 s66, s84, s49
	s_mov_b32 s65, 0
	s_addc_u32 s67, s85, 0
	s_movk_i32 s49, 0xffe0
	s_movk_i32 s64, 0xf000
	s_mov_b32 s79, 0
	s_branch .LBB0_157
